# attention: static s_setprio 1 for waves 4-7 in the tile loop + K swizzle fix
# baseline (speedup 1.0000x reference)
; __device__ __forceinline__ int v_st(int k, int c) { const int kk = (k & ~0xC) | ((k & 4) << 1) | ((k & 8) >> 1); return ((kk >> 3) * 4 + (c >> 5)) * 512 + ((kk & 7) * 32 + (c & 31)) * 2; }
; __device__ __forceinline__ int v_rd_base(int lane) { return ((lane & 3) << 3) | (((lane >> 2) & 3) << 6) | (((lane >> 4) & 1) << 5) | (((lane >> 5) & 1) << 8); }
; __device__ __forceinline__ void qkt(f32x16& p0, f32x16& p1, const bf16* Ks, const bf16x8* qr, int r32, int hi) {
;   p0 = f32x16{}; p1 = f32x16{};
;   for (int d0 = 0; d0 < 8; ++d0) { int cb = (d0 * 16 + hi * 8) * 2;
;     bf16x8 b0 = *reinterpret_cast<const bf16x8*>((const char*)Ks + KSWZ(r32, cb));
;     bf16x8 b1 = *reinterpret_cast<const bf16x8*>((const char*)Ks + KSWZ(32 + r32, cb));
;     p0 = __builtin_amdgcn_mfma_f32_32x32x16_bf16(b0, qr[d0], p0, 0, 0, 0);
;     p1 = __builtin_amdgcn_mfma_f32_32x32x16_bf16(b1, qr[d0], p1, 0, 0, 0); }
; template <typename TQ>
; __device__ __forceinline__ void attn_dense_body(const TQ* __restrict__ Qb, const bf16* __restrict__ Kh, const bf16* __restrict__ Vh,
;                                                 bf16* __restrict__ Ob, int seq, char* lds, const int tid) {
;     ...
;   const int wid = __builtin_amdgcn_readfirstlane(tid >> 6), lane = tid & 63, r32 = lane & 31, hi = lane >> 5;
;   bf16* V_lds = (bf16*)lds; bf16* K_lds = (bf16*)(lds + 2 * SHM_V);
;   float* ws = (float*)(lds + 2 * SHM_V + 2 * SHM_K) + wid * 64; float* li_l = ws; float* al_l = ws + 32;
;   float m_reg = -1e30f, l_reg = 0; f32x16 o[4] = {}; bf16x8 qr[8];
;   const TQ* Qw = Qb + (long)(wid * QBLK + r32) * LDQ + hi * 8;
; #pragma unroll
;   for (int d0 = 0; d0 < 8; ++d0) qr[d0] = SQ::tobf(SQ::ld8(Qw + d0 * 16));
;   const int sr = tid >> 4, sc = (tid & 15) * 8, vst0 = v_st(sr, sc), vst1 = v_st(32 + sr, sc);
;   const int vb0 = (int)(uintptr_t)V_lds + v_rd_base(lane);
;   struct { typename St::T vs0, vs1, ks0, ks1; } sr_[SDEPTH];
;     ...
;   f32x16 pA0, pA1, pB0, pB1; float mnA, mnB, alA, alB; bf16x8 pa0, pa1, pa2, pa3; const int NT = seq / KVBLK;
;   constexpr int SE = 0, SO = SDEPTH - 1;
;   SLOAD(SE, 0); asm volatile("s_waitcnt vmcnt(0)" ::: "memory"); SWRITE(0, SE); __syncthreads();
;   qkt(pA0, pA1, K_lds, qr, r32, hi); partialSM(pA0, pA1, m_reg, mnA, alA);
.LBB0_1528:
	s_lshr_b32 s5, s2, 4
	s_ashr_i32 s4, s2, 7
	s_bfe_u32 s16, s5, 0x10002
	s_ashr_i32 s5, s4, 31
	s_lshl_b64 s[6:7], s[4:5], 12
	s_lshl_b32 s5, s2, 8
	s_and_b32 s5, s5, 0xf00
	s_bfe_u32 s8, s2, 0x30004
	s_or_b32 s5, s6, s5
	s_add_u32 s18, s5, 0x800
	s_addc_u32 s19, s7, 0
	s_mul_i32 s5, s19, 0xc00
	s_mul_hi_u32 s6, s18, 0xc00
	s_add_i32 s6, s6, s5
	s_mul_i32 s5, s18, 0xc00
	s_add_u32 s5, s24, s5
	s_addc_u32 s6, s25, s6
	s_lshl_b32 s15, s8, 7
	s_lshl_b32 s7, s8, 8
	s_add_u32 s8, s5, s7
	s_addc_u32 s9, s6, 0
	s_lshl_b32 s4, s4, 1
	v_mbcnt_lo_u32_b32 v0, -1, 0
	v_mbcnt_hi_u32_b32 v0, -1, v0
	s_or_b32 s16, s16, s4
	v_add_u32_e32 v52, s74, v0
	s_mul_i32 s6, s16, 0x110000
	v_readlane_b32 s4, v254, 14
	v_ashrrev_i32_e32 v16, 4, v52
	s_mul_hi_i32 s7, s16, 0x110000
	v_readlane_b32 s5, v254, 15
	s_add_u32 s4, s4, s6
	v_lshlrev_b32_e32 v22, 3, v52
	v_add_u32_e32 v18, 32, v16
	s_addc_u32 s5, s5, s7
	v_and_b32_e32 v0, 0x78, v22
	v_ashrrev_i32_e32 v17, 31, v16
	v_ashrrev_i32_e32 v19, 31, v18
	s_add_u32 s6, s3, s6
	v_lshlrev_b32_e32 v23, 1, v0
	v_lshlrev_b64 v[48:49], 8, v[16:17]
	s_waitcnt vmcnt(8)
	v_lshlrev_b64 v[12:13], 8, v[18:19]
	s_addc_u32 s7, s11, s7
	v_or_b32_e32 v50, v48, v23
	v_mov_b32_e32 v51, v49
	v_or_b32_e32 v12, v12, v23
	v_lshl_add_u64 v[0:1], s[6:7], 0, v[50:51]
	v_lshl_add_u64 v[4:5], s[6:7], 0, v[12:13]
	s_barrier
	global_load_dwordx4 v[0:3], v[0:1], off
	s_nop 0
	global_load_dwordx4 v[4:7], v[4:5], off
	v_lshl_add_u64 v[8:9], s[4:5], 0, v[50:51]
	global_load_dwordx4 v[8:11], v[8:9], off
	v_lshl_add_u64 v[12:13], s[4:5], 0, v[12:13]
	v_readfirstlane_b32 s17, v52
	global_load_dwordx4 v[12:15], v[12:13], off
	s_ashr_i32 s20, s17, 1
	v_mov_b32_e32 v17, s20
	s_movk_i32 s21, 0xffe0
	v_bfe_u32 v182, v52, 5, 1
	v_bfi_b32 v17, s21, v17, v52
	v_mov_b64_e32 v[20:21], s[8:9]
	s_movk_i32 s8, 0xc00
	v_mad_i64_i32 v[20:21], s[8:9], v17, s8, v[20:21]
	v_lshlrev_b32_e32 v176, 4, v182
	v_lshl_add_u64 v[20:21], v[20:21], 0, v[176:177]
	global_load_dwordx4 v[120:123], v[20:21], off
	global_load_dwordx4 v[112:115], v[20:21], off offset:32
	global_load_dwordx4 v[124:127], v[20:21], off offset:64
	global_load_dwordx4 v[116:119], v[20:21], off offset:96
	global_load_dwordx4 v[108:111], v[20:21], off offset:128
	global_load_dwordx4 v[104:107], v[20:21], off offset:160
	global_load_dwordx4 v[100:103], v[20:21], off offset:192
	global_load_dwordx4 v[96:99], v[20:21], off offset:224
	v_and_b32_e32 v17, 0xfffff0, v16
	v_lshlrev_b32_e32 v19, 1, v16
	v_lshrrev_b32_e32 v24, 1, v16
	v_and_b32_e32 v25, 3, v16
	v_and_or_b32 v17, v19, 8, v17
	v_and_or_b32 v19, v24, 4, v25
	v_and_b32_e32 v24, 0xfffff0, v18
	v_lshlrev_b32_e32 v25, 1, v18
	v_bfe_u32 v22, v22, 5, 2
	v_lshrrev_b32_e32 v17, 1, v17
	v_and_or_b32 v24, v25, 8, v24
	v_or_b32_e32 v17, v17, v22
	v_lshrrev_b32_e32 v24, 1, v24
	v_lshlrev_b32_e32 v19, 6, v19
	v_and_b32_e32 v26, 48, v23
	v_lshlrev_b32_e32 v17, 9, v17
	v_or_b32_e32 v22, v24, v22
	v_or3_b32 v17, v17, v19, v26
	v_lshlrev_b32_e32 v22, 9, v22
	v_or3_b32 v19, v22, v19, v26
	v_add_u32_e32 v188, 0, v17
	v_add_u32_e32 v189, 0, v19
	s_waitcnt vmcnt(0)
	v_and_b32_e32 v183, 31, v52
	v_lshlrev_b32_e32 v53, 4, v52
	v_and_b32_e32 v76, 63, v52
	s_mov_b64 s[36:37], 0x4000
	v_lshl_add_u64 v[62:63], v[50:51], 0, s[36:37]
	s_mov_b64 s[36:37], 0x6000
	s_waitcnt vmcnt(11)
	ds_write_b128 v188, v[0:3]
	s_waitcnt vmcnt(10)
	ds_write_b128 v189, v[4:7]
	v_lshlrev_b32_e32 v0, 8, v16
	v_and_b32_e32 v1, 0xf0, v52
	v_bitop3_b32 v0, v23, v0, v1 bitop3:0xde
	v_add_u32_e32 v190, 0, v0
	v_lshlrev_b32_e32 v0, 8, v18
	s_waitcnt vmcnt(9)
	ds_write_b128 v190, v[8:11] offset:32768
	v_bitop3_b32 v0, v23, v0, v1 bitop3:0xde
	v_lshlrev_b32_e32 v8, 8, v183
	v_and_b32_e32 v9, 0xf0, v53
	v_add_u32_e32 v191, 0, v0
	v_bitop3_b32 v0, v176, v8, v9 bitop3:0xde
	v_add_u32_e32 v192, 0, v0
	s_waitcnt vmcnt(8)
	ds_write_b128 v191, v[12:15] offset:32768
	s_waitcnt lgkmcnt(0)
	s_barrier
	ds_read_b128 v[0:3], v192 offset:32768
	ds_read_b128 v[4:7], v192 offset:40960
	s_waitcnt vmcnt(7) lgkmcnt(1)
	v_mfma_f32_32x32x16_bf16 v[32:47], v[0:3], v[120:123], 0
	v_or_b32_e32 v0, 32, v176
	v_bitop3_b32 v0, v0, v8, v9 bitop3:0xde
	v_add_u32_e32 v199, 0, v0
	v_lshlrev_b32_e32 v10, 3, v76
	v_lshlrev_b32_e32 v12, 1, v52
	v_lshl_add_u64 v[64:65], v[50:51], 0, s[36:37]
	v_lshl_add_u64 v[58:59], s[6:7], 0, v[64:65]
	s_waitcnt lgkmcnt(0)
	v_mfma_f32_32x32x16_bf16 v[16:31], v[4:7], v[120:123], 0
	ds_read_b128 v[0:3], v199 offset:32768
	ds_read_b128 v[4:7], v199 offset:40960
	v_lshl_add_u64 v[66:67], s[4:5], 0, v[64:65]
	s_mov_b64 s[36:37], 0xa000
	s_and_b32 s8, s17, 0x3fffffc0
	s_lshl_b32 s8, s8, 2
	s_add_i32 s8, s8, 0
	s_add_i32 s8, s8, 0x10000
	s_waitcnt vmcnt(6) lgkmcnt(1)
	v_mfma_f32_32x32x16_bf16 v[32:47], v[0:3], v[112:115], v[32:47]
	v_or_b32_e32 v0, 64, v176
	v_bitop3_b32 v0, v0, v8, v9 bitop3:0xde
	v_add_u32_e32 v198, 0, v0
	s_andn2_b32 s20, s20, 31
	s_cmp_lg_u32 0, -1
	s_cselect_b32 s9, 0, 0
	s_mov_b32 s57, s56
	s_waitcnt lgkmcnt(0)
	v_mfma_f32_32x32x16_bf16 v[16:31], v[4:7], v[112:115], v[16:31]
	ds_read_b128 v[0:3], v198 offset:32768
	ds_read_b128 v[4:7], v198 offset:40960
	s_mov_b32 s58, s56
	s_mov_b32 s59, s56
	s_mov_b32 s60, s56
	s_mov_b32 s61, s56
	s_mov_b32 s62, s56
	s_mov_b32 s63, s56
	s_waitcnt vmcnt(5) lgkmcnt(1)
	v_mfma_f32_32x32x16_bf16 v[32:47], v[0:3], v[124:127], v[32:47]
	v_or_b32_e32 v0, 0x60, v176
	v_bitop3_b32 v0, v0, v8, v9 bitop3:0xde
	v_add_u32_e32 v195, 0, v0
	s_mov_b32 s64, s56
	s_mov_b32 s65, s56
	s_mov_b32 s66, s56
	s_mov_b32 s67, s56
	s_waitcnt lgkmcnt(0)
; #define SLOAD(i, k0) do { sr_[i].vs0 = St::ld8(&Vh[(long)((k0) + sr) * LDK + sc]); sr_[i].vs1 = St::ld8(&Vh[(long)((k0) + 32 + sr) * LDK + sc]); \
;     sr_[i].ks0 = St::ld8(&Kh[(long)((k0) + sr) * LDK + sc]); sr_[i].ks1 = St::ld8(&Kh[(long)((k0) + 32 + sr) * LDK + sc]); } while (0)
; __device__ __forceinline__ void qkt(f32x16& p0, f32x16& p1, const bf16* Ks, const bf16x8* qr, int r32, int hi) {
;   p0 = f32x16{}; p1 = f32x16{};
;   for (int d0 = 0; d0 < 8; ++d0) { int cb = (d0 * 16 + hi * 8) * 2;
;     bf16x8 b0 = *reinterpret_cast<const bf16x8*>((const char*)Ks + KSWZ(r32, cb));
;     bf16x8 b1 = *reinterpret_cast<const bf16x8*>((const char*)Ks + KSWZ(32 + r32, cb));
;     p0 = __builtin_amdgcn_mfma_f32_32x32x16_bf16(b0, qr[d0], p0, 0, 0, 0);
;     p1 = __builtin_amdgcn_mfma_f32_32x32x16_bf16(b1, qr[d0], p1, 0, 0, 0); }
; }
; template <typename TQ>
; __device__ __forceinline__ void attn_dense_body(const TQ* __restrict__ Qb, const bf16* __restrict__ Kh, const bf16* __restrict__ Vh,
;                                                 bf16* __restrict__ Ob, int seq, char* lds, const int tid) {
;     ...
;   qkt(pA0, pA1, K_lds, qr, r32, hi); partialSM(pA0, pA1, m_reg, mnA, alA);
;   SLOAD(SO, KVBLK); if constexpr (SDEPTH == 2) { if (2 < NT) SLOAD(SE, 2 * KVBLK); }
	v_mfma_f32_32x32x16_bf16 v[16:31], v[4:7], v[124:127], v[16:31]
	ds_read_b128 v[0:3], v195 offset:32768
	ds_read_b128 v[4:7], v195 offset:40960
	s_mov_b32 s68, s56
	s_mov_b32 s69, s56
	s_mov_b32 s70, s56
	s_mov_b32 s71, s56
	v_lshl_add_u32 v184, v183, 2, s8
	v_mov_b32_e32 v185, 0
	s_waitcnt vmcnt(4) lgkmcnt(1)
	v_mfma_f32_32x32x16_bf16 v[32:47], v[0:3], v[116:119], v[32:47]
	v_or_b32_e32 v0, 0x80, v176
	v_bitop3_b32 v0, v0, v8, v9 bitop3:0xde
	v_add_u32_e32 v194, 0, v0
	s_waitcnt lgkmcnt(0)
	v_mfma_f32_32x32x16_bf16 v[16:31], v[4:7], v[116:119], v[16:31]
	ds_read_b128 v[0:3], v194 offset:32768
	ds_read_b128 v[4:7], v194 offset:40960
	s_waitcnt vmcnt(3) lgkmcnt(1)
	v_mfma_f32_32x32x16_bf16 v[32:47], v[0:3], v[108:111], v[32:47]
	v_or_b32_e32 v0, 0xa0, v176
	v_bitop3_b32 v0, v0, v8, v9 bitop3:0xde
	v_add_u32_e32 v193, 0, v0
	ds_read_b128 v[0:3], v193 offset:32768
	s_waitcnt lgkmcnt(1)
	v_mfma_f32_32x32x16_bf16 v[16:31], v[4:7], v[108:111], v[16:31]
	ds_read_b128 v[4:7], v193 offset:40960
	s_waitcnt vmcnt(2) lgkmcnt(1)
	v_mfma_f32_32x32x16_bf16 v[32:47], v[0:3], v[104:107], v[32:47]
	v_and_b32_e32 v0, 0xc0, v53
	v_and_or_b32 v11, v10, 24, v0
	v_or_b32_e32 v0, 0xc0, v176
	v_bitop3_b32 v0, v0, v8, v9 bitop3:0xde
	v_add_u32_e32 v196, 0, v0
	ds_read_b128 v[0:3], v196 offset:32768
	s_waitcnt lgkmcnt(1)
	v_mfma_f32_32x32x16_bf16 v[16:31], v[4:7], v[104:107], v[16:31]
	v_and_b32_e32 v4, 32, v12
	v_and_b32_e32 v5, 0x100, v10
	v_or3_b32 v53, v11, v4, v5
	ds_read_b128 v[4:7], v196 offset:40960
	v_add_u32_e32 v187, s9, v53
	s_waitcnt vmcnt(1) lgkmcnt(1)
	v_mfma_f32_32x32x16_bf16 v[32:47], v[0:3], v[100:103], v[32:47]
	v_or_b32_e32 v0, 0xe0, v176
	v_bitop3_b32 v0, v0, v8, v9 bitop3:0xde
	v_add_u32_e32 v197, 0, v0
	ds_read_b128 v[0:3], v197 offset:32768
	ds_read_b128 v[54:57], v197 offset:40960
	s_waitcnt lgkmcnt(2)
	v_mfma_f32_32x32x16_bf16 v[16:31], v[4:7], v[100:103], v[16:31]
	s_waitcnt vmcnt(0) lgkmcnt(1)
	v_mfma_f32_32x32x16_bf16 v[32:47], v[0:3], v[96:99], v[32:47]
	v_mov_b64_e32 v[0:1], s[56:57]
	v_mov_b64_e32 v[14:15], s[70:71]
	v_mov_b64_e32 v[2:3], s[58:59]
	v_mov_b64_e32 v[4:5], s[60:61]
	v_mov_b64_e32 v[6:7], s[62:63]
	v_mov_b64_e32 v[8:9], s[64:65]
	v_mov_b64_e32 v[10:11], s[66:67]
	s_waitcnt lgkmcnt(0)
	v_mfma_f32_32x32x16_bf16 v[16:31], v[54:57], v[96:99], v[16:31]
	s_nop 2
	v_max_f32_e32 v54, v33, v33
	v_max_f32_e32 v55, v32, v32
	v_max_f32_e32 v54, v55, v54
	v_max3_f32 v54, v54, v34, v35
	v_max3_f32 v54, v54, v36, v37
	v_max3_f32 v54, v54, v38, v39
	v_max3_f32 v54, v54, v40, v41
	v_max3_f32 v54, v54, v42, v43
	v_max3_f32 v54, v54, v44, v45
	v_max3_f32 v54, v54, v46, v47
	v_max3_f32 v70, v54, v16, v17
	v_max3_f32 v70, v70, v18, v19
	v_max3_f32 v70, v70, v20, v21
	v_max3_f32 v70, v70, v22, v23
	v_max3_f32 v70, v70, v24, v25
	v_max3_f32 v70, v70, v26, v27
	v_lshl_add_u64 v[54:55], s[6:7], 0, v[62:63]
	v_lshl_add_u64 v[62:63], s[4:5], 0, v[62:63]
	v_max3_f32 v70, v70, v28, v29
	global_load_dwordx4 v[54:57], v[54:55], off
	s_nop 0
	global_load_dwordx4 v[58:61], v[58:59], off
	s_nop 0
	global_load_dwordx4 v[62:65], v[62:63], off
	s_nop 0
	global_load_dwordx4 v[66:69], v[66:67], off
	v_max3_f32 v77, v70, v30, v31
	v_lshl_add_u64 v[70:71], v[50:51], 0, s[12:13]
	v_lshl_add_u64 v[72:73], s[6:7], 0, v[70:71]
	v_lshl_add_u64 v[50:51], v[50:51], 0, s[36:37]
	v_lshl_add_u64 v[70:71], s[4:5], 0, v[70:71]
	v_lshl_add_u64 v[74:75], s[6:7], 0, v[50:51]
	global_load_dwordx4 v[128:131], v[72:73], off
	global_load_dwordx4 v[136:139], v[74:75], off
	v_lshl_add_u64 v[50:51], s[4:5], 0, v[50:51]
	global_load_dwordx4 v[132:135], v[70:71], off
	global_load_dwordx4 v[140:143], v[50:51], off
	v_mov_b32_e32 v78, v77
	s_nop 1
	v_permlane32_swap_b32_e32 v77, v78
	v_max_f32_e32 v50, v78, v78
	v_max_f32_e32 v51, v77, v77
	v_max_f32_e32 v50, v51, v50
	v_add_f32_e32 v51, 0x7149f2ca, v50
	v_max_f32_e32 v50, 0xf149f2ca, v50
	v_cmp_ge_f32_e32 vcc, s14, v51
	v_sub_f32_e32 v51, 0xf149f2ca, v50
	v_mul_f32_e32 v51, 0x3e0293ee, v51
	v_exp_f32_e32 v51, v51
	s_cmp_eq_u64 vcc, exec
	s_cselect_b64 vcc, -1, 0
	v_cndmask_b32_e32 v164, v50, v180, vcc
	v_mul_f32_e32 v50, 0xbe0293ee, v164
	v_cndmask_b32_e64 v200, v51, 1.0, vcc
	v_mov_b32_e32 v51, v50
	v_fmamk_f32 v32, v32, 0x3e0293ee, v50
	v_fmamk_f32 v33, v33, 0x3e0293ee, v50
	v_fmamk_f32 v34, v34, 0x3e0293ee, v50
	v_fmamk_f32 v35, v35, 0x3e0293ee, v50
	v_fmamk_f32 v36, v36, 0x3e0293ee, v50
	v_fmamk_f32 v37, v37, 0x3e0293ee, v50
	v_fmamk_f32 v38, v38, 0x3e0293ee, v50
	v_fmamk_f32 v39, v39, 0x3e0293ee, v50
	v_fmamk_f32 v40, v40, 0x3e0293ee, v50
	v_fmamk_f32 v41, v41, 0x3e0293ee, v50
	v_fmamk_f32 v42, v42, 0x3e0293ee, v50
	v_fmamk_f32 v43, v43, 0x3e0293ee, v50
	v_fmamk_f32 v44, v44, 0x3e0293ee, v50
	v_fmamk_f32 v45, v45, 0x3e0293ee, v50
	v_fmamk_f32 v46, v46, 0x3e0293ee, v50
	v_fmac_f32_e32 v51, 0x3e0293ee, v47
	v_pk_fma_f32 v[154:155], v[18:19], s[10:11], v[50:51] op_sel_hi:[1,0,0]
	v_pk_fma_f32 v[156:157], v[16:17], s[10:11], v[50:51] op_sel_hi:[1,0,0]
	v_exp_f32_e32 v161, v32
	v_exp_f32_e32 v162, v33
	v_exp_f32_e32 v174, v34
	v_exp_f32_e32 v175, v35
	v_exp_f32_e32 v204, v36
	v_exp_f32_e32 v207, v37
	v_exp_f32_e32 v163, v38
	v_exp_f32_e32 v173, v39
	v_exp_f32_e32 v168, v40
	v_exp_f32_e32 v170, v41
	v_exp_f32_e32 v171, v42
	v_exp_f32_e32 v172, v43
	v_exp_f32_e32 v165, v44
	v_exp_f32_e32 v166, v45
	v_exp_f32_e32 v167, v46
	v_exp_f32_e32 v169, v51
	v_mad_i64_i32 v[16:17], s[4:5], s16, v181, v[48:49]
	v_and_b32_e32 v18, 15, v52
	s_waitcnt vmcnt(4)
; #define SBAR() __builtin_amdgcn_sched_barrier(0)
; #define SLOAD(i, k0) do { sr_[i].vs0 = St::ld8(&Vh[(long)((k0) + sr) * LDK + sc]); sr_[i].vs1 = St::ld8(&Vh[(long)((k0) + 32 + sr) * LDK + sc]); \
;     sr_[i].ks0 = St::ld8(&Kh[(long)((k0) + sr) * LDK + sc]); sr_[i].ks1 = St::ld8(&Kh[(long)((k0) + 32 + sr) * LDK + sc]); } while (0)
; #define SWAIT() do { if constexpr (SDEPTH == 2) asm volatile("s_waitcnt vmcnt(4)" ::: "memory"); else asm volatile("s_waitcnt vmcnt(0)" ::: "memory"); } while (0)
; template <typename TQ>
; __device__ __forceinline__ void attn_dense_body(const TQ* __restrict__ Qb, const bf16* __restrict__ Kh, const bf16* __restrict__ Vh,
;                                                 bf16* __restrict__ Ob, int seq, char* lds, const int tid) {
;     ...
;   SWAIT(); SWRITE(1, SO); __syncthreads();
;   for (int j = 1; j + 1 < NT; j += 2) {
;     SBAR(); qkt(pB0, pB1, (bf16*)((char*)K_lds + SHM_K), qr, r32, hi);
;     finishSM(pA0, pA1, alA, l_reg, pa0, pa1, pa2, pa3); SBAR();
;     SLOAD(SO, (j + SDEPTH) * KVBLK); SBAR();
	s_addk_i32 s9, 0x4000
	v_lshl_or_b32 v16, v18, 4, v16
	v_mov_b64_e32 v[12:13], s[68:69]
	v_pk_fma_f32 v[150:151], v[30:31], s[10:11], v[50:51] op_sel_hi:[1,0,0]
	v_pk_fma_f32 v[152:153], v[28:29], s[10:11], v[50:51] op_sel_hi:[1,0,0]
	v_pk_fma_f32 v[158:159], v[26:27], s[10:11], v[50:51] op_sel_hi:[1,0,0]
	v_pk_fma_f32 v[144:145], v[24:25], s[10:11], v[50:51] op_sel_hi:[1,0,0]
	v_pk_fma_f32 v[146:147], v[22:23], s[10:11], v[50:51] op_sel_hi:[1,0,0]
	v_pk_fma_f32 v[148:149], v[20:21], s[10:11], v[50:51] op_sel_hi:[1,0,0]
	s_waitcnt vmcnt(7)
	ds_write_b128 v188, v[54:57] offset:16384
	s_waitcnt vmcnt(6)
	ds_write_b128 v189, v[58:61] offset:16384
	s_waitcnt vmcnt(5)
	ds_write_b128 v190, v[62:65] offset:49152
	s_waitcnt vmcnt(4)
	ds_write_b128 v191, v[66:69] offset:49152
	v_add_u32_e32 v186, s9, v53
	v_lshl_add_u64 v[178:179], s[0:1], 0, v[16:17]
	v_mov_b64_e32 v[62:63], v[14:15]
	v_mov_b64_e32 v[46:47], v[14:15]
	v_mov_b64_e32 v[30:31], v[14:15]
	v_cmp_gt_u32_e64 s[36:37], 32, v76
	v_mov_b64_e32 v[60:61], v[12:13]
	v_mov_b64_e32 v[58:59], v[10:11]
	v_mov_b64_e32 v[56:57], v[8:9]
	v_mov_b64_e32 v[54:55], v[6:7]
	v_mov_b64_e32 v[52:53], v[4:5]
	v_mov_b64_e32 v[50:51], v[2:3]
	v_mov_b64_e32 v[48:49], v[0:1]
	v_mov_b64_e32 v[44:45], v[12:13]
	v_mov_b64_e32 v[42:43], v[10:11]
	v_mov_b64_e32 v[40:41], v[8:9]
	v_mov_b64_e32 v[38:39], v[6:7]
	v_mov_b64_e32 v[36:37], v[4:5]
	v_mov_b64_e32 v[34:35], v[2:3]
	v_mov_b64_e32 v[32:33], v[0:1]
	v_mov_b64_e32 v[28:29], v[12:13]
	v_mov_b64_e32 v[26:27], v[10:11]
	v_mov_b64_e32 v[24:25], v[8:9]
	v_mov_b64_e32 v[22:23], v[6:7]
	v_mov_b64_e32 v[20:21], v[4:5]
	v_mov_b64_e32 v[18:19], v[2:3]
	v_mov_b64_e32 v[16:17], v[0:1]
	s_mov_b32 s9, 1
	s_waitcnt lgkmcnt(0)
	s_barrier
	s_cmp_ge_u32 s17, 0x100
	s_cbranch_scc0 .Latt_prio_done
	s_setprio 1
.Latt_prio_done:
.LBB0_1529:
	ds_read_b128 v[64:67], v192 offset:49152
	ds_read_b128 v[68:71], v192 offset:57344
	ds_read_b128 v[208:211], v199 offset:49152
	ds_read_b128 v[212:215], v199 offset:57344
	v_add_f32_e32 v160, 0, v161
	v_add_f32_e32 v160, v162, v160
	s_waitcnt lgkmcnt(3)
	v_mfma_f32_32x32x16_bf16 v[80:95], v[64:67], v[120:123], 0
	v_add_f32_e32 v160, v174, v160
	v_add_f32_e32 v160, v175, v160
	v_add_f32_e32 v160, v204, v160
	v_add_f32_e32 v160, v207, v160
	v_add_f32_e32 v160, v163, v160
	v_add_f32_e32 v160, v173, v160
	v_add_f32_e32 v160, v168, v160
	s_waitcnt lgkmcnt(2)
	v_mfma_f32_32x32x16_bf16 v[64:79], v[68:71], v[120:123], 0
	v_add_f32_e32 v160, v170, v160
	v_add_f32_e32 v160, v171, v160
	v_add_f32_e32 v160, v172, v160
	v_exp_f32_e32 v156, v156
	v_add_f32_e32 v160, v165, v160
	v_exp_f32_e32 v157, v157
	v_add_f32_e32 v160, v166, v160
	s_waitcnt lgkmcnt(1)
	v_mfma_f32_32x32x16_bf16 v[80:95], v[208:211], v[112:115], v[80:95]
	v_exp_f32_e32 v154, v154
	v_add_f32_e32 v160, v167, v160
	v_exp_f32_e32 v155, v155
	v_add_f32_e32 v160, v169, v160
	v_exp_f32_e32 v148, v148
	v_add_f32_e32 v160, v156, v160
	v_exp_f32_e32 v149, v149
	s_waitcnt lgkmcnt(0)
	v_mfma_f32_32x32x16_bf16 v[64:79], v[212:215], v[112:115], v[64:79]
	ds_read_b128 v[208:211], v198 offset:49152
	ds_read_b128 v[212:215], v198 offset:57344
	v_add_f32_e32 v160, v157, v160
	v_exp_f32_e32 v146, v146
	v_add_f32_e32 v160, v154, v160
	v_exp_f32_e32 v147, v147
	v_add_f32_e32 v160, v155, v160
	v_exp_f32_e32 v144, v144
	s_waitcnt lgkmcnt(1)
	v_mfma_f32_32x32x16_bf16 v[80:95], v[208:211], v[124:127], v[80:95]
	v_add_f32_e32 v160, v148, v160
	v_exp_f32_e32 v145, v145
	v_add_f32_e32 v160, v149, v160
	v_exp_f32_e32 v158, v158
	v_add_f32_e32 v160, v146, v160
	v_exp_f32_e32 v159, v159
	v_add_f32_e32 v160, v147, v160
	s_waitcnt lgkmcnt(0)
	v_mfma_f32_32x32x16_bf16 v[64:79], v[212:215], v[124:127], v[64:79]
	ds_read_b128 v[208:211], v195 offset:49152
	ds_read_b128 v[212:215], v195 offset:57344
	v_exp_f32_e32 v152, v152
	v_add_f32_e32 v160, v144, v160
	v_exp_f32_e32 v153, v153
	v_add_f32_e32 v160, v145, v160
	v_exp_f32_e32 v150, v150
	v_add_f32_e32 v160, v158, v160
	s_waitcnt lgkmcnt(1)
	v_mfma_f32_32x32x16_bf16 v[80:95], v[208:211], v[116:119], v[80:95]
	v_exp_f32_e32 v151, v151
	v_add_f32_e32 v160, v159, v160
	v_add_f32_e32 v160, v152, v160
	v_add_f32_e32 v160, v153, v160
	v_add_f32_e32 v160, v150, v160
	v_add_f32_e32 v201, v151, v160
	v_mov_b32_e32 v202, v201
	s_waitcnt lgkmcnt(0)
	v_mfma_f32_32x32x16_bf16 v[64:79], v[212:215], v[116:119], v[64:79]
	ds_read_b128 v[208:211], v194 offset:49152
	ds_read_b128 v[212:215], v194 offset:57344
	v_cvt_pk_bf16_f32 v160, v161, v162
	v_cvt_pk_bf16_f32 v162, v204, v207
	v_permlane32_swap_b32_e32 v201, v202
	v_cvt_pk_bf16_f32 v161, v174, v175
	v_cvt_pk_bf16_f32 v163, v163, v173
	s_waitcnt lgkmcnt(1)
	v_mfma_f32_32x32x16_bf16 v[80:95], v[208:211], v[108:111], v[80:95]
	v_permlane32_swap_b32_e32 v160, v162
	v_cvt_pk_bf16_f32 v170, v168, v170
	v_cvt_pk_bf16_f32 v171, v171, v172
	v_cvt_pk_bf16_f32 v172, v165, v166
	v_cvt_pk_bf16_f32 v173, v167, v169
	v_cvt_pk_bf16_f32 v166, v156, v157
	s_waitcnt lgkmcnt(0)
	v_mfma_f32_32x32x16_bf16 v[64:79], v[212:215], v[108:111], v[64:79]
	ds_read_b128 v[208:211], v193 offset:49152
	ds_read_b128 v[212:215], v193 offset:57344
	v_cvt_pk_bf16_f32 v167, v154, v155
	v_cvt_pk_bf16_f32 v168, v148, v149
	v_cvt_pk_bf16_f32 v169, v146, v147
	v_cvt_pk_bf16_f32 v204, v144, v145
	v_cvt_pk_bf16_f32 v205, v158, v159
	v_cvt_pk_bf16_f32 v206, v152, v153
	s_waitcnt lgkmcnt(1)
	v_mfma_f32_32x32x16_bf16 v[80:95], v[208:211], v[104:107], v[80:95]
	v_cvt_pk_bf16_f32 v207, v150, v151
	v_permlane32_swap_b32_e32 v161, v163
	v_permlane32_swap_b32_e32 v170, v172
	v_permlane32_swap_b32_e32 v171, v173
	s_waitcnt lgkmcnt(0)
; #define SBAR() __builtin_amdgcn_sched_barrier(0)
; #define SLOAD(i, k0) do { sr_[i].vs0 = St::ld8(&Vh[(long)((k0) + sr) * LDK + sc]); sr_[i].vs1 = St::ld8(&Vh[(long)((k0) + 32 + sr) * LDK + sc]); \
;     sr_[i].ks0 = St::ld8(&Kh[(long)((k0) + sr) * LDK + sc]); sr_[i].ks1 = St::ld8(&Kh[(long)((k0) + 32 + sr) * LDK + sc]); } while (0)
; #define SWAIT() do { if constexpr (SDEPTH == 2) asm volatile("s_waitcnt vmcnt(4)" ::: "memory"); else asm volatile("s_waitcnt vmcnt(0)" ::: "memory"); } while (0)
; template <typename TQ>
; __device__ __forceinline__ void attn_dense_body(const TQ* __restrict__ Qb, const bf16* __restrict__ Kh, const bf16* __restrict__ Vh,
;                                                 bf16* __restrict__ Ob, int seq, char* lds, const int tid) {
;     ...
;     SBAR(); qkt(pB0, pB1, (bf16*)((char*)K_lds + SHM_K), qr, r32, hi);
;     finishSM(pA0, pA1, alA, l_reg, pa0, pa1, pa2, pa3); SBAR();
;     SLOAD(SO, (j + SDEPTH) * KVBLK); SBAR();
;     pv_d0(o, vb0, pa0, pa1, pa2, pa3); partialSM(pB0, pB1, m_reg, mnB, alB);
;     __syncthreads(); SWAIT(); SWRITE(0, SE);
	v_mfma_f32_32x32x16_bf16 v[64:79], v[212:215], v[104:107], v[64:79]
	ds_read_b128 v[208:211], v196 offset:49152
	ds_read_b128 v[212:215], v196 offset:57344
	v_permlane32_swap_b32_e32 v166, v168
	v_permlane32_swap_b32_e32 v167, v169
	v_permlane32_swap_b32_e32 v204, v206
	s_waitcnt lgkmcnt(1)
	v_mfma_f32_32x32x16_bf16 v[80:95], v[208:211], v[100:103], v[80:95]
	v_permlane32_swap_b32_e32 v205, v207
	s_waitcnt lgkmcnt(0)
	v_mfma_f32_32x32x16_bf16 v[64:79], v[212:215], v[100:103], v[64:79]
	ds_read_b128 v[208:211], v197 offset:49152
	ds_read_b128 v[212:215], v197 offset:57344
	s_waitcnt lgkmcnt(1)
	v_mfma_f32_32x32x16_bf16 v[80:95], v[208:211], v[96:99], v[80:95]
	s_waitcnt lgkmcnt(0)
	v_mfma_f32_32x32x16_bf16 v[64:79], v[212:215], v[96:99], v[64:79]
	s_movk_i32 s4, 0xa000
	v_add_co_u32_e32 v144, vcc, s4, v178
	s_movk_i32 s4, 0xc000
	s_nop 0
	v_addc_co_u32_e32 v145, vcc, -1, v179, vcc
	v_add_co_u32_e32 v148, vcc, s4, v178
	s_mov_b32 s4, 0xe53fa000
	s_nop 0
	v_addc_co_u32_e32 v149, vcc, -1, v179, vcc
	v_add_co_u32_e32 v152, vcc, s4, v178
	s_mov_b32 s4, 0xe53fc000
	s_nop 0
	v_addc_co_u32_e32 v153, vcc, -1, v179, vcc
	v_add_co_u32_e32 v156, vcc, s4, v178
	global_load_dwordx4 v[144:147], v[144:145], off
	s_nop 0
	global_load_dwordx4 v[148:151], v[148:149], off
	v_addc_co_u32_e32 v157, vcc, -1, v179, vcc
	global_load_dwordx4 v[152:155], v[152:153], off
	s_nop 0
	global_load_dwordx4 v[156:159], v[156:157], off
	ds_read_b64_tr_b16 v[208:209], v187 offset:0
	ds_read_b64_tr_b16 v[210:211], v187 offset:0x800
	ds_read_b64_tr_b16 v[212:213], v187 offset:0x1000
	ds_read_b64_tr_b16 v[214:215], v187 offset:0x1800
	ds_read_b64_tr_b16 v[218:219], v187 offset:0x2000
	ds_read_b64_tr_b16 v[220:221], v187 offset:0x2800
	ds_read_b64_tr_b16 v[222:223], v187 offset:0x3000
	ds_read_b64_tr_b16 v[224:225], v187 offset:0x3800
	s_waitcnt lgkmcnt(0)
	s_nop 0
	v_mfma_f32_32x32x16_bf16 v[0:15], v[160:163], v[208:211], v[0:15]
	ds_read_b64_tr_b16 v[208:209], v187 offset:0x200
	ds_read_b64_tr_b16 v[210:211], v187 offset:0xa00
	v_mfma_f32_32x32x16_bf16 v[0:15], v[170:173], v[212:215], v[0:15]
	ds_read_b64_tr_b16 v[212:213], v187 offset:0x1200
	ds_read_b64_tr_b16 v[214:215], v187 offset:0x1a00
	v_mfma_f32_32x32x16_bf16 v[0:15], v[166:169], v[218:221], v[0:15]
	ds_read_b64_tr_b16 v[218:219], v187 offset:0x2200
	ds_read_b64_tr_b16 v[220:221], v187 offset:0x2a00
	v_mfma_f32_32x32x16_bf16 v[0:15], v[204:207], v[222:225], v[0:15]
	ds_read_b64_tr_b16 v[222:223], v187 offset:0x3200
	ds_read_b64_tr_b16 v[224:225], v187 offset:0x3a00
	s_waitcnt lgkmcnt(0)
	v_mfma_f32_32x32x16_bf16 v[48:63], v[160:163], v[208:211], v[48:63]
	ds_read_b64_tr_b16 v[208:209], v187 offset:0x400
	ds_read_b64_tr_b16 v[210:211], v187 offset:0xc00
	v_mfma_f32_32x32x16_bf16 v[48:63], v[170:173], v[212:215], v[48:63]
	ds_read_b64_tr_b16 v[212:213], v187 offset:0x1400
	ds_read_b64_tr_b16 v[214:215], v187 offset:0x1c00
	v_mfma_f32_32x32x16_bf16 v[48:63], v[166:169], v[218:221], v[48:63]
	ds_read_b64_tr_b16 v[218:219], v187 offset:0x2400
	ds_read_b64_tr_b16 v[220:221], v187 offset:0x2c00
	v_mfma_f32_32x32x16_bf16 v[48:63], v[204:207], v[222:225], v[48:63]
	ds_read_b64_tr_b16 v[222:223], v187 offset:0x3400
	ds_read_b64_tr_b16 v[224:225], v187 offset:0x3c00
	s_waitcnt lgkmcnt(0)
	v_mfma_f32_32x32x16_bf16 v[32:47], v[160:163], v[208:211], v[32:47]
	ds_read_b64_tr_b16 v[208:209], v187 offset:0x600
	ds_read_b64_tr_b16 v[210:211], v187 offset:0xe00
	v_mfma_f32_32x32x16_bf16 v[32:47], v[170:173], v[212:215], v[32:47]
	ds_read_b64_tr_b16 v[212:213], v187 offset:0x1600
	ds_read_b64_tr_b16 v[214:215], v187 offset:0x1e00
	v_mfma_f32_32x32x16_bf16 v[32:47], v[166:169], v[218:221], v[32:47]
	ds_read_b64_tr_b16 v[218:219], v187 offset:0x2600
	ds_read_b64_tr_b16 v[220:221], v187 offset:0x2e00
	v_mfma_f32_32x32x16_bf16 v[32:47], v[204:207], v[222:225], v[32:47]
	ds_read_b64_tr_b16 v[222:223], v187 offset:0x3600
	ds_read_b64_tr_b16 v[224:225], v187 offset:0x3e00
	s_waitcnt lgkmcnt(0)
	v_mfma_f32_32x32x16_bf16 v[16:31], v[160:163], v[208:211], v[16:31]
	v_max_f32_e32 v160, v81, v81
	v_max_f32_e32 v161, v80, v80
	v_max_f32_e32 v160, v161, v160
	v_max3_f32 v160, v160, v82, v83
	v_max3_f32 v160, v160, v84, v85
	v_max3_f32 v160, v160, v86, v87
	v_max3_f32 v160, v160, v88, v89
	v_max3_f32 v160, v160, v90, v91
	v_max3_f32 v160, v160, v92, v93
	v_mfma_f32_32x32x16_bf16 v[16:31], v[170:173], v[212:215], v[16:31]
	v_max3_f32 v160, v160, v94, v95
	v_max3_f32 v160, v160, v64, v65
	v_max3_f32 v160, v160, v66, v67
	v_max3_f32 v160, v160, v68, v69
	v_max3_f32 v160, v160, v70, v71
	v_max3_f32 v160, v160, v72, v73
	v_max3_f32 v160, v160, v74, v75
	v_max3_f32 v160, v160, v76, v77
	v_mfma_f32_32x32x16_bf16 v[16:31], v[166:169], v[218:221], v[16:31]
	v_max3_f32 v160, v160, v78, v79
	v_mov_b32_e32 v161, v160
	s_nop 1
	v_permlane32_swap_b32_e32 v160, v161
	v_max_f32_e32 v161, v161, v161
	v_max_f32_e32 v160, v160, v160
	v_max_f32_e32 v160, v160, v161
	v_sub_f32_e32 v161, v160, v164
	v_cmp_ge_f32_e32 vcc, s14, v161
	v_max_f32_e32 v161, v164, v164
	v_max_f32_e32 v160, v161, v160
	v_mfma_f32_32x32x16_bf16 v[16:31], v[204:207], v[222:225], v[16:31]
	v_sub_f32_e32 v161, v164, v160
	v_mul_f32_e32 v161, 0x3e0293ee, v161
	v_exp_f32_e32 v161, v161
	s_cmp_eq_u64 vcc, exec
	s_cselect_b64 s[38:39], -1, 0
	s_barrier
; #define SWAIT() do { if constexpr (SDEPTH == 2) asm volatile("s_waitcnt vmcnt(4)" ::: "memory"); else asm volatile("s_waitcnt vmcnt(0)" ::: "memory"); } while (0)
; #define RESC(a) do { if (__any((a) < 1.f)) { if (hi == 0) al_l[r32] = (a); asm volatile("s_waitcnt lgkmcnt(0)" ::: "memory"); \
;     for (int d = 0; d < 4; ++d) for (int r = 0; r < 16; ++r) o[d][r] *= al_l[crow(r, hi)]; } } while (0)
; template <typename TQ>
; __device__ __forceinline__ void attn_dense_body(const TQ* __restrict__ Qb, const bf16* __restrict__ Kh, const bf16* __restrict__ Vh,
;                                                 bf16* __restrict__ Ob, int seq, char* lds, const int tid) {
;     ...
;     __syncthreads(); SWAIT(); SWRITE(0, SE);
;     RESC(alB); __syncthreads();
	s_waitcnt vmcnt(4)
	v_cndmask_b32_e64 v203, v161, 1.0, s[38:39]
	v_cmp_gt_f32_e32 vcc, 1.0, v203
	s_waitcnt vmcnt(7)
	ds_write_b128 v188, v[128:131]
	s_waitcnt vmcnt(6)
	ds_write_b128 v189, v[136:139]
	s_waitcnt vmcnt(5)
	ds_write_b128 v190, v[132:135] offset:32768
	s_waitcnt vmcnt(4)
	ds_write_b128 v191, v[140:143] offset:32768
	s_cbranch_vccz .LBB0_1533
	s_and_saveexec_b64 s[4:5], s[36:37]
	ds_write_b32 v184, v203 offset:128
	s_or_b64 exec, exec, s[4:5]
	s_waitcnt lgkmcnt(0)
	v_add_u32_e32 v161, s8, v176
	ds_read_b128 v[166:169], v161 offset:224
	ds_read_b128 v[170:173], v161 offset:192
	ds_read_b128 v[204:207], v161 offset:160
	ds_read_b128 v[208:211], v161 offset:128
	s_waitcnt lgkmcnt(3)
	v_pk_mul_f32 v[12:13], v[12:13], v[166:167]
	s_waitcnt lgkmcnt(2)
	v_pk_mul_f32 v[8:9], v[8:9], v[170:171]
	s_waitcnt lgkmcnt(1)
	v_pk_mul_f32 v[4:5], v[4:5], v[204:205]
	v_pk_mul_f32 v[14:15], v[14:15], v[168:169]
	v_pk_mul_f32 v[10:11], v[10:11], v[172:173]
	v_pk_mul_f32 v[6:7], v[6:7], v[206:207]
	s_waitcnt lgkmcnt(0)
	v_pk_mul_f32 v[2:3], v[2:3], v[210:211]
	v_pk_mul_f32 v[0:1], v[0:1], v[208:209]
	v_pk_mul_f32 v[60:61], v[60:61], v[166:167]
	v_pk_mul_f32 v[56:57], v[56:57], v[170:171]
	v_pk_mul_f32 v[52:53], v[52:53], v[204:205]
	v_pk_mul_f32 v[62:63], v[62:63], v[168:169]
	v_pk_mul_f32 v[58:59], v[58:59], v[172:173]
	v_pk_mul_f32 v[54:55], v[54:55], v[206:207]
	v_pk_mul_f32 v[50:51], v[50:51], v[210:211]
	v_pk_mul_f32 v[48:49], v[48:49], v[208:209]
	v_pk_mul_f32 v[44:45], v[44:45], v[166:167]
	v_pk_mul_f32 v[40:41], v[40:41], v[170:171]
	v_pk_mul_f32 v[36:37], v[36:37], v[204:205]
	v_pk_mul_f32 v[46:47], v[46:47], v[168:169]
	v_pk_mul_f32 v[42:43], v[42:43], v[172:173]
	v_pk_mul_f32 v[38:39], v[38:39], v[206:207]
	v_pk_mul_f32 v[34:35], v[34:35], v[210:211]
	v_pk_mul_f32 v[32:33], v[32:33], v[208:209]
	v_pk_mul_f32 v[28:29], v[28:29], v[166:167]
	v_pk_mul_f32 v[24:25], v[24:25], v[170:171]
	v_pk_mul_f32 v[20:21], v[20:21], v[204:205]
	v_pk_mul_f32 v[30:31], v[30:31], v[168:169]
	v_pk_mul_f32 v[26:27], v[26:27], v[172:173]
	v_pk_mul_f32 v[22:23], v[22:23], v[206:207]
	v_pk_mul_f32 v[18:19], v[18:19], v[210:211]
	v_pk_mul_f32 v[16:17], v[16:17], v[208:209]

; #define SBAR() __builtin_amdgcn_sched_barrier(0)
; #define RESC(a) do { if (__any((a) < 1.f)) { if (hi == 0) al_l[r32] = (a); asm volatile("s_waitcnt lgkmcnt(0)" ::: "memory"); \
;     for (int d = 0; d < 4; ++d) for (int r = 0; r < 16; ++r) o[d][r] *= al_l[crow(r, hi)]; } } while (0)
; template <typename TQ>
; __device__ __forceinline__ void attn_dense_body(const TQ* __restrict__ Qb, const bf16* __restrict__ Kh, const bf16* __restrict__ Vh,
;                                                 bf16* __restrict__ Ob, int seq, char* lds, const int tid) {
;     ...
;   SBAR(); qkt(pB0, pB1, (bf16*)((char*)K_lds + SHM_K), qr, r32, hi);
;   finishSM(pA0, pA1, alA, l_reg, pa0, pa1, pa2, pa3); SBAR();
;   pv_d0(o, vb0, pa0, pa1, pa2, pa3); partialSM(pB0, pB1, m_reg, mnB, alB);
;   __syncthreads(); RESC(alB);
;   finishSM(pB0, pB1, alB, l_reg, pa0, pa1, pa2, pa3); SBAR();
;   pv_d0(o, vb0 + (int)SHM_V, pa0, pa1, pa2, pa3);
.LBB0_1541:
	s_setprio 0
	ds_read_b128 v[64:67], v192 offset:49152
	ds_read_b128 v[68:71], v192 offset:57344
	s_waitcnt lgkmcnt(1)
	v_mfma_f32_32x32x16_bf16 v[80:95], v[64:67], v[120:123], 0
	s_waitcnt lgkmcnt(0)
	v_mfma_f32_32x32x16_bf16 v[64:79], v[68:71], v[120:123], 0
	ds_read_b128 v[120:123], v199 offset:49152
	ds_read_b128 v[128:131], v199 offset:57344
	s_waitcnt lgkmcnt(1)
	v_mfma_f32_32x32x16_bf16 v[80:95], v[120:123], v[112:115], v[80:95]
	s_waitcnt lgkmcnt(0)
	v_mfma_f32_32x32x16_bf16 v[64:79], v[128:131], v[112:115], v[64:79]
	ds_read_b128 v[112:115], v198 offset:49152
	ds_read_b128 v[120:123], v198 offset:57344
	s_waitcnt lgkmcnt(1)
	v_mfma_f32_32x32x16_bf16 v[80:95], v[112:115], v[124:127], v[80:95]
	s_waitcnt lgkmcnt(0)
	v_mfma_f32_32x32x16_bf16 v[64:79], v[120:123], v[124:127], v[64:79]
	ds_read_b128 v[112:115], v195 offset:49152
	ds_read_b128 v[120:123], v195 offset:57344
	s_waitcnt lgkmcnt(1)
	v_mfma_f32_32x32x16_bf16 v[80:95], v[112:115], v[116:119], v[80:95]
	s_waitcnt lgkmcnt(0)
	v_mfma_f32_32x32x16_bf16 v[64:79], v[120:123], v[116:119], v[64:79]
	ds_read_b128 v[112:115], v194 offset:49152
	ds_read_b128 v[116:119], v194 offset:57344
	v_exp_f32_e32 v120, v150
	v_exp_f32_e32 v121, v151
	s_waitcnt lgkmcnt(1)
	v_mfma_f32_32x32x16_bf16 v[80:95], v[112:115], v[108:111], v[80:95]
	s_waitcnt lgkmcnt(0)
	v_mfma_f32_32x32x16_bf16 v[64:79], v[116:119], v[108:111], v[64:79]
	ds_read_b128 v[108:111], v193 offset:49152
	ds_read_b128 v[112:115], v193 offset:57344
	v_exp_f32_e32 v116, v158
	v_exp_f32_e32 v117, v159
	v_exp_f32_e32 v118, v152
	v_exp_f32_e32 v119, v153
	s_waitcnt lgkmcnt(1)
	v_mfma_f32_32x32x16_bf16 v[80:95], v[108:111], v[104:107], v[80:95]
	s_waitcnt lgkmcnt(0)
	v_mfma_f32_32x32x16_bf16 v[64:79], v[112:115], v[104:107], v[64:79]
	ds_read_b128 v[104:107], v196 offset:49152
	ds_read_b128 v[108:111], v196 offset:57344
	v_exp_f32_e32 v112, v146
	v_exp_f32_e32 v113, v147
	v_exp_f32_e32 v114, v144
	v_exp_f32_e32 v115, v145
	s_waitcnt lgkmcnt(1)
	v_mfma_f32_32x32x16_bf16 v[80:95], v[104:107], v[100:103], v[80:95]
	s_waitcnt lgkmcnt(0)
	v_mfma_f32_32x32x16_bf16 v[64:79], v[108:111], v[100:103], v[64:79]
	ds_read_b128 v[100:103], v197 offset:49152
	ds_read_b128 v[104:107], v197 offset:57344
	v_exp_f32_e32 v108, v154
	v_exp_f32_e32 v109, v155
	v_exp_f32_e32 v110, v148
	v_exp_f32_e32 v111, v149
	s_waitcnt lgkmcnt(1)
	v_mfma_f32_32x32x16_bf16 v[80:95], v[100:103], v[96:99], v[80:95]
	v_cvt_pk_bf16_f32 v100, v204, v207
	v_cvt_pk_bf16_f32 v101, v163, v173
	v_cvt_pk_bf16_f32 v102, v168, v170
	v_cvt_pk_bf16_f32 v103, v171, v172
	s_waitcnt lgkmcnt(0)
	v_mfma_f32_32x32x16_bf16 v[64:79], v[104:107], v[96:99], v[64:79]
	v_add_f32_e32 v96, 0, v161
	v_add_f32_e32 v96, v162, v96
	v_add_f32_e32 v96, v174, v96
	v_add_f32_e32 v96, v175, v96
	v_add_f32_e32 v96, v204, v96
	v_add_f32_e32 v96, v207, v96
	v_add_f32_e32 v96, v163, v96
	v_add_f32_e32 v96, v173, v96
	v_add_f32_e32 v96, v168, v96
	v_add_f32_e32 v96, v170, v96
	v_add_f32_e32 v96, v171, v96
	v_add_f32_e32 v96, v172, v96
	v_exp_f32_e32 v106, v156
	v_add_f32_e32 v96, v165, v96
	v_exp_f32_e32 v107, v157
	v_add_f32_e32 v96, v166, v96
	v_add_f32_e32 v96, v167, v96
	v_add_f32_e32 v96, v169, v96
	v_add_f32_e32 v96, v106, v96
	v_add_f32_e32 v96, v107, v96
	v_add_f32_e32 v96, v108, v96
	v_add_f32_e32 v96, v109, v96
	v_add_f32_e32 v96, v110, v96
	v_add_f32_e32 v96, v111, v96
	v_add_f32_e32 v96, v112, v96
	v_add_f32_e32 v96, v113, v96
	v_add_f32_e32 v96, v114, v96
	v_add_f32_e32 v96, v115, v96
	v_add_f32_e32 v96, v116, v96
	v_add_f32_e32 v96, v117, v96
	v_add_f32_e32 v96, v118, v96
	v_add_f32_e32 v96, v119, v96
	v_add_f32_e32 v96, v120, v96
	v_add_f32_e32 v96, v121, v96
	v_mov_b32_e32 v97, v96
	v_cvt_pk_bf16_f32 v98, v161, v162
	v_cvt_pk_bf16_f32 v99, v174, v175
	v_permlane32_swap_b32_e32 v96, v97
	v_permlane32_swap_b32_e32 v98, v100
	v_permlane32_swap_b32_e32 v99, v101
	v_cvt_pk_bf16_f32 v104, v165, v166
	v_cvt_pk_bf16_f32 v105, v167, v169
	v_cvt_pk_bf16_f32 v106, v106, v107
	v_cvt_pk_bf16_f32 v107, v108, v109
	v_cvt_pk_bf16_f32 v108, v110, v111
	v_cvt_pk_bf16_f32 v109, v112, v113
	v_cvt_pk_bf16_f32 v110, v114, v115
	v_cvt_pk_bf16_f32 v111, v116, v117
	v_cvt_pk_bf16_f32 v112, v118, v119
	v_cvt_pk_bf16_f32 v113, v120, v121
	v_permlane32_swap_b32_e32 v102, v104
	v_permlane32_swap_b32_e32 v103, v105
	v_permlane32_swap_b32_e32 v106, v108
	v_permlane32_swap_b32_e32 v107, v109
	v_permlane32_swap_b32_e32 v110, v112
	v_permlane32_swap_b32_e32 v111, v113
	ds_read_b64_tr_b16 v[114:115], v187 offset:0
	ds_read_b64_tr_b16 v[116:117], v187 offset:0x800
	ds_read_b64_tr_b16 v[118:119], v187 offset:0x1000
	ds_read_b64_tr_b16 v[120:121], v187 offset:0x1800
	ds_read_b64_tr_b16 v[122:123], v187 offset:0x2000
	ds_read_b64_tr_b16 v[124:125], v187 offset:0x2800
	ds_read_b64_tr_b16 v[126:127], v187 offset:0x3000
	ds_read_b64_tr_b16 v[128:129], v187 offset:0x3800
	s_waitcnt lgkmcnt(0)
; #define RESC(a) do { if (__any((a) < 1.f)) { if (hi == 0) al_l[r32] = (a); asm volatile("s_waitcnt lgkmcnt(0)" ::: "memory"); \
;     for (int d = 0; d < 4; ++d) for (int r = 0; r < 16; ++r) o[d][r] *= al_l[crow(r, hi)]; } } while (0)
; template <typename TQ>
; __device__ __forceinline__ void attn_dense_body(const TQ* __restrict__ Qb, const bf16* __restrict__ Kh, const bf16* __restrict__ Vh,
;                                                 bf16* __restrict__ Ob, int seq, char* lds, const int tid) {
;     ...
;   pv_d0(o, vb0, pa0, pa1, pa2, pa3); partialSM(pB0, pB1, m_reg, mnB, alB);
;   __syncthreads(); RESC(alB);
	s_nop 0
	v_mfma_f32_32x32x16_bf16 v[0:15], v[98:101], v[114:117], v[0:15]
	ds_read_b64_tr_b16 v[114:115], v187 offset:0x200
	ds_read_b64_tr_b16 v[116:117], v187 offset:0xa00
	v_mfma_f32_32x32x16_bf16 v[0:15], v[102:105], v[118:121], v[0:15]
	ds_read_b64_tr_b16 v[118:119], v187 offset:0x1200
	ds_read_b64_tr_b16 v[120:121], v187 offset:0x1a00
	v_mfma_f32_32x32x16_bf16 v[0:15], v[106:109], v[122:125], v[0:15]
	ds_read_b64_tr_b16 v[122:123], v187 offset:0x2200
	ds_read_b64_tr_b16 v[124:125], v187 offset:0x2a00
	v_mfma_f32_32x32x16_bf16 v[0:15], v[110:113], v[126:129], v[0:15]
	ds_read_b64_tr_b16 v[126:127], v187 offset:0x3200
	ds_read_b64_tr_b16 v[128:129], v187 offset:0x3a00
	s_waitcnt lgkmcnt(0)
	v_mfma_f32_32x32x16_bf16 v[48:63], v[98:101], v[114:117], v[48:63]
	ds_read_b64_tr_b16 v[114:115], v187 offset:0x400
	ds_read_b64_tr_b16 v[116:117], v187 offset:0xc00
	v_mfma_f32_32x32x16_bf16 v[48:63], v[102:105], v[118:121], v[48:63]
	ds_read_b64_tr_b16 v[118:119], v187 offset:0x1400
	ds_read_b64_tr_b16 v[120:121], v187 offset:0x1c00
	v_mfma_f32_32x32x16_bf16 v[48:63], v[106:109], v[122:125], v[48:63]
	ds_read_b64_tr_b16 v[122:123], v187 offset:0x2400
	ds_read_b64_tr_b16 v[124:125], v187 offset:0x2c00
	v_mfma_f32_32x32x16_bf16 v[48:63], v[110:113], v[126:129], v[48:63]
	ds_read_b64_tr_b16 v[126:127], v187 offset:0x3400
	ds_read_b64_tr_b16 v[128:129], v187 offset:0x3c00
	s_waitcnt lgkmcnt(0)
	v_mfma_f32_32x32x16_bf16 v[32:47], v[98:101], v[114:117], v[32:47]
	ds_read_b64_tr_b16 v[114:115], v187 offset:0x600
	ds_read_b64_tr_b16 v[116:117], v187 offset:0xe00
	v_mfma_f32_32x32x16_bf16 v[32:47], v[102:105], v[118:121], v[32:47]
	ds_read_b64_tr_b16 v[118:119], v187 offset:0x1600
	ds_read_b64_tr_b16 v[120:121], v187 offset:0x1e00
	v_mfma_f32_32x32x16_bf16 v[32:47], v[106:109], v[122:125], v[32:47]
	ds_read_b64_tr_b16 v[122:123], v187 offset:0x2600
	ds_read_b64_tr_b16 v[124:125], v187 offset:0x2e00
	v_mfma_f32_32x32x16_bf16 v[32:47], v[110:113], v[126:129], v[32:47]
	ds_read_b64_tr_b16 v[126:127], v187 offset:0x3600
	ds_read_b64_tr_b16 v[128:129], v187 offset:0x3e00
	s_waitcnt lgkmcnt(0)
	v_mfma_f32_32x32x16_bf16 v[16:31], v[98:101], v[114:117], v[16:31]
	v_max_f32_e32 v98, v81, v81
	v_max_f32_e32 v99, v80, v80
	v_max_f32_e32 v98, v99, v98
	v_max3_f32 v98, v98, v82, v83
	v_max3_f32 v98, v98, v84, v85
	v_max3_f32 v98, v98, v86, v87
	v_max3_f32 v98, v98, v88, v89
	v_max3_f32 v98, v98, v90, v91
	v_max3_f32 v98, v98, v92, v93
	v_mfma_f32_32x32x16_bf16 v[16:31], v[102:105], v[118:121], v[16:31]
	v_max3_f32 v98, v98, v94, v95
	v_max3_f32 v98, v98, v64, v65
	v_max3_f32 v98, v98, v66, v67
	v_max3_f32 v98, v98, v68, v69
	v_max3_f32 v98, v98, v70, v71
	v_max3_f32 v98, v98, v72, v73
	v_max3_f32 v98, v98, v74, v75
	v_max3_f32 v98, v98, v76, v77
	v_mfma_f32_32x32x16_bf16 v[16:31], v[106:109], v[122:125], v[16:31]
	v_max3_f32 v98, v98, v78, v79
	v_mov_b32_e32 v99, v98
	s_nop 1
	v_permlane32_swap_b32_e32 v98, v99
	v_max_f32_e32 v99, v99, v99
	v_max_f32_e32 v98, v98, v98
	v_max_f32_e32 v98, v98, v99
	v_sub_f32_e32 v99, v98, v164
	v_cmp_ge_f32_e32 vcc, s14, v99
	v_max_f32_e32 v99, v164, v164
	v_max_f32_e32 v99, v99, v98
	v_mfma_f32_32x32x16_bf16 v[16:31], v[110:113], v[126:129], v[16:31]
	v_sub_f32_e32 v98, v164, v99
	v_mul_f32_e32 v98, 0x3e0293ee, v98
	v_exp_f32_e32 v98, v98
	s_cmp_eq_u64 vcc, exec
	s_cselect_b64 s[38:39], -1, 0
	v_cndmask_b32_e64 v98, v98, 1.0, s[38:39]
	v_cmp_gt_f32_e32 vcc, 1.0, v98
	s_barrier
	s_cbranch_vccz .LBB0_1545
	s_and_saveexec_b64 s[4:5], s[36:37]
	ds_write_b32 v184, v98 offset:128
	s_or_b64 exec, exec, s[4:5]
	s_waitcnt lgkmcnt(0)
	v_add_u32_e32 v112, s8, v176
	ds_read_b128 v[100:103], v112 offset:224
	ds_read_b128 v[104:107], v112 offset:192
	ds_read_b128 v[108:111], v112 offset:160
	ds_read_b128 v[112:115], v112 offset:128
	s_waitcnt lgkmcnt(3)
	v_pk_mul_f32 v[12:13], v[12:13], v[100:101]
	s_waitcnt lgkmcnt(2)
	v_pk_mul_f32 v[8:9], v[8:9], v[104:105]
	s_waitcnt lgkmcnt(1)
	v_pk_mul_f32 v[4:5], v[4:5], v[108:109]
	v_pk_mul_f32 v[14:15], v[14:15], v[102:103]
	v_pk_mul_f32 v[10:11], v[10:11], v[106:107]
	v_pk_mul_f32 v[6:7], v[6:7], v[110:111]
	s_waitcnt lgkmcnt(0)
	v_pk_mul_f32 v[2:3], v[2:3], v[114:115]
	v_pk_mul_f32 v[0:1], v[0:1], v[112:113]
	v_pk_mul_f32 v[60:61], v[60:61], v[100:101]
	v_pk_mul_f32 v[56:57], v[56:57], v[104:105]
	v_pk_mul_f32 v[52:53], v[52:53], v[108:109]
	v_pk_mul_f32 v[62:63], v[62:63], v[102:103]
	v_pk_mul_f32 v[58:59], v[58:59], v[106:107]
	v_pk_mul_f32 v[54:55], v[54:55], v[110:111]
	v_pk_mul_f32 v[50:51], v[50:51], v[114:115]
	v_pk_mul_f32 v[48:49], v[48:49], v[112:113]
	v_pk_mul_f32 v[44:45], v[44:45], v[100:101]
	v_pk_mul_f32 v[40:41], v[40:41], v[104:105]
	v_pk_mul_f32 v[36:37], v[36:37], v[108:109]
	v_pk_mul_f32 v[46:47], v[46:47], v[102:103]
	v_pk_mul_f32 v[42:43], v[42:43], v[106:107]
	v_pk_mul_f32 v[38:39], v[38:39], v[110:111]
	v_pk_mul_f32 v[34:35], v[34:35], v[114:115]
	v_pk_mul_f32 v[32:33], v[32:33], v[112:113]
	v_pk_mul_f32 v[28:29], v[28:29], v[100:101]
	v_pk_mul_f32 v[24:25], v[24:25], v[104:105]
	v_pk_mul_f32 v[20:21], v[20:21], v[108:109]
	v_pk_mul_f32 v[30:31], v[30:31], v[102:103]
	v_pk_mul_f32 v[26:27], v[26:27], v[106:107]
	v_pk_mul_f32 v[22:23], v[22:23], v[110:111]
	v_pk_mul_f32 v[18:19], v[18:19], v[114:115]
	v_pk_mul_f32 v[16:17], v[16:17], v[112:113]
